# pass-B quad sums via DPP instead of LDS permutes; row-max xor-32 via permlane32_swap; FoX loop vote with one barrier per tile (rotating LDS words)
# speedup vs baseline: 1.1314x; 1.0145x over previous
.LBB0_286:
	s_or_b64 exec, exec, s[82:83]
	s_lshl_b32 s26, s46, 3
	v_mov_b32_e32 v8, s26
	global_load_dwordx2 v[8:9], v8, s[68:69]
	v_and_b32_e32 v12, 0xffff0000, v64
	v_lshlrev_b32_e32 v10, 16, v64
	v_mul_f32_e32 v12, v12, v12
	v_lshlrev_b32_e32 v13, 16, v65
	v_fmac_f32_e32 v12, v10, v10
	v_and_b32_e32 v14, 0xffff0000, v65
	v_fmac_f32_e32 v12, v13, v13
	v_lshlrev_b32_e32 v15, 16, v66
	v_fmac_f32_e32 v12, v14, v14
	v_and_b32_e32 v16, 0xffff0000, v66
	v_fmac_f32_e32 v12, v15, v15
	v_lshlrev_b32_e32 v17, 16, v67
	v_fmac_f32_e32 v12, v16, v16
	v_and_b32_e32 v18, 0xffff0000, v67
	v_fmac_f32_e32 v12, v17, v17
	v_lshlrev_b32_e32 v19, 16, v68
	v_fmac_f32_e32 v12, v18, v18
	v_and_b32_e32 v20, 0xffff0000, v68
	v_fmac_f32_e32 v12, v19, v19
	v_lshlrev_b32_e32 v21, 16, v69
	v_fmac_f32_e32 v12, v20, v20
	v_and_b32_e32 v22, 0xffff0000, v69
	v_fmac_f32_e32 v12, v21, v21
	v_lshlrev_b32_e32 v23, 16, v70
	v_fmac_f32_e32 v12, v22, v22
	v_and_b32_e32 v24, 0xffff0000, v70
	v_fmac_f32_e32 v12, v23, v23
	v_lshlrev_b32_e32 v25, 16, v71
	v_fmac_f32_e32 v12, v24, v24
	v_and_b32_e32 v26, 0xffff0000, v71
	v_fmac_f32_e32 v12, v25, v25
	v_lshlrev_b32_e32 v27, 16, v72
	v_fmac_f32_e32 v12, v26, v26
	v_and_b32_e32 v28, 0xffff0000, v72
	v_fmac_f32_e32 v12, v27, v27
	v_lshlrev_b32_e32 v29, 16, v73
	v_fmac_f32_e32 v12, v28, v28
	v_and_b32_e32 v30, 0xffff0000, v73
	v_fmac_f32_e32 v12, v29, v29
	v_lshlrev_b32_e32 v31, 16, v74
	v_fmac_f32_e32 v12, v30, v30
	v_and_b32_e32 v32, 0xffff0000, v74
	v_fmac_f32_e32 v12, v31, v31
	v_lshlrev_b32_e32 v33, 16, v75
	v_fmac_f32_e32 v12, v32, v32
	v_and_b32_e32 v34, 0xffff0000, v75
	v_fmac_f32_e32 v12, v33, v33
	v_lshlrev_b32_e32 v35, 16, v76
	v_fmac_f32_e32 v12, v34, v34
	v_and_b32_e32 v36, 0xffff0000, v76
	v_fmac_f32_e32 v12, v35, v35
	v_lshlrev_b32_e32 v37, 16, v77
	v_fmac_f32_e32 v12, v36, v36
	v_and_b32_e32 v38, 0xffff0000, v77
	v_fmac_f32_e32 v12, v37, v37
	v_lshlrev_b32_e32 v39, 16, v78
	v_fmac_f32_e32 v12, v38, v38
	v_and_b32_e32 v42, 0xffff0000, v78
	v_xor_b32_e32 v45, 32, v211
	v_add_u32_e32 v41, 64, v41
	v_fmac_f32_e32 v12, v39, v39
	v_lshlrev_b32_e32 v43, 16, v79
	v_cmp_lt_i32_e32 vcc, v45, v41
	v_fmac_f32_e32 v12, v42, v42
	v_and_b32_e32 v44, 0xffff0000, v79
	v_cndmask_b32_e32 v41, v211, v45, vcc
	v_fmac_f32_e32 v12, v43, v43
	v_lshlrev_b32_e32 v113, 2, v41
	v_fmac_f32_e32 v12, v44, v44
	s_or_b32 s26, s48, 0x80
	ds_bpermute_b32 v13, v113, v12
	v_or_b32_e32 v45, s26, v109
	v_mov_b32_e32 v11, v97
	v_lshlrev_b32_e32 v10, 11, v45
	s_mov_b32 s51, s73
	v_lshl_add_u64 v[10:11], s[22:23], 0, v[10:11]
	v_lshl_add_u64 v[10:11], v[10:11], 0, s[50:51]
	global_load_dwordx4 v[80:83], v[10:11], off
	s_waitcnt lgkmcnt(0)
	v_add_f32_e32 v10, v12, v13
	s_waitcnt vmcnt(1)
	v_add_f32_e32 v8, v8, v9
	v_mul_f32_e32 v8, v10, v8
	s_mov_b32 s22, 0xf800000
	v_mul_f32_e32 v9, 0x4f800000, v8
	v_cmp_gt_f32_e32 vcc, s22, v8
	s_mov_b32 s53, s73
	v_mov_b32_e32 v41, v97
	v_cndmask_b32_e32 v8, v8, v9, vcc
	v_sqrt_f32_e32 v9, v8
	v_lshlrev_b32_e32 v114, 2, v111
	s_lshr_b32 s49, s45, 6
	s_or_b32 s46, s80, 31
	v_add_u32_e32 v10, -1, v9
	v_fma_f32 v11, -v10, v9, v8
	v_cmp_ge_f32_e64 s[22:23], 0, v11
	v_add_u32_e32 v11, 1, v9
	v_mov_b32_e32 v14, v97
	v_cndmask_b32_e64 v10, v9, v10, s[22:23]
	v_fma_f32 v9, -v11, v9, v8
	v_cmp_lt_f32_e64 s[22:23], 0, v9
	v_mov_b32_e32 v15, v97
	v_mov_b32_e32 v12, v97
	v_cndmask_b32_e64 v9, v10, v11, s[22:23]
	v_mul_f32_e32 v10, 0x37800000, v9
	v_readlane_b32 s22, v254, 19
	v_cndmask_b32_e32 v9, v9, v10, vcc
	v_cmp_class_f32_e32 vcc, v8, v104
	s_or_b32 s22, s22, s26
	v_readlane_b32 s26, v254, 17
	v_cndmask_b32_e32 v10, v9, v8, vcc
	v_or_b32_e32 v8, s22, v47
	v_lshlrev_b32_e32 v8, 11, v8
	v_mov_b32_e32 v9, v97
	v_lshl_add_u64 v[8:9], s[24:25], 0, v[8:9]
	v_lshl_add_u64 v[8:9], v[8:9], 0, s[52:53]
	v_lshl_add_u64 v[8:9], v[8:9], 0, v[40:41]
	global_load_dwordx4 v[92:95], v[8:9], off
	v_lshlrev_b32_e32 v8, 1, v46
	v_and_b32_e32 v116, 32, v8
	v_lshrrev_b32_e32 v8, 2, v46
	v_and_or_b32 v8, v8, 3, v114
	v_lshlrev_b32_e32 v117, 6, v8
	v_lshlrev_b32_e32 v8, 4, v109
	v_readlane_b32 s22, v254, 16
	v_cmp_eq_u32_e32 vcc, 0, v211
	v_add_u32_e32 v121, s26, v8
	v_add_u32_e32 v9, s22, v8
	ds_write_b128 v9, v[0:3]
	ds_write_b128 v9, v[4:7] offset:8192
	v_mov_b32_e32 v250, 0x21a00
	v_mov_b32_e32 v251, 1
	ds_write_b32 v250, v251
	ds_write_b32 v250, v251 offset:4
	ds_write_b32 v250, v251 offset:8
	s_mov_b32 s98, 0
	s_waitcnt lgkmcnt(0)
	s_barrier
	s_load_dwordx2 s[22:23], s[94:95], 0xc
	v_fmamk_f32 v115, v10, 0x3f8020c5, v105
	v_mov_b32_e32 v2, v97
	v_mov_b32_e32 v3, v97
	v_mov_b32_e32 v4, v97
	s_waitcnt lgkmcnt(0)
	s_lshr_b32 s24, s22, 16
	s_and_b32 s22, s22, 0xffff
	s_mul_i32 s25, s24, s22
	s_and_b32 s23, s23, 0xffff
	s_bfe_i32 s25, s25, 0x180000
	s_mul_i32 s23, s25, s23
	s_add_i32 s23, s23, 63
	s_andn2_b32 s23, s23, 63
	v_mad_u32_u24 v0, v161, s24, v210
	s_cmp_lg_u32 s23, 64
	v_mad_u64_u32 v[0:1], s[22:23], v0, s22, v[160:161]
	v_lshrrev_b32_e32 v1, 6, v0
	s_cselect_b64 s[82:83], -1, 0
	v_or_b32_e32 v1, v1, v211
	v_cmp_lt_u32_e64 s[24:25], 63, v0
	s_lshl_b32 s26, s47, 7
	v_and_b32_e32 v0, 3, v46
	s_add_i32 s27, s30, s48
	v_cmp_eq_u32_e64 s[22:23], 0, v1
	s_and_b64 s[24:25], vcc, s[24:25]
	s_and_b32 s26, s26, 0x780
	v_lshlrev_b32_e32 v0, 4, v0
	v_add_lshl_u32 v1, s27, v47, 11
	s_add_i32 s27, s48, 64
	v_or3_b32 v0, s26, v0, v1
	v_mov_b32_e32 v1, v97
	s_add_u32 s84, s33, s26
	v_lshl_add_u64 v[100:101], s[74:75], 0, v[0:1]
	v_add_lshl_u32 v0, s27, v109, 11
	s_addc_u32 s85, s35, 0
	s_lshl_b32 s26, s48, 2
	v_lshl_add_u64 v[102:103], s[84:85], 0, v[0:1]
	s_addk_i32 s26, 0x100
	v_mov_b32_e32 v0, v97
	v_mov_b32_e32 v5, v97
	v_mov_b32_e32 v6, v97
	v_mov_b32_e32 v7, v97
	v_mov_b32_e32 v8, v97
	v_mov_b32_e32 v9, v97
	v_mov_b32_e32 v10, v97
	v_mov_b32_e32 v11, v97
	v_mov_b32_e32 v13, v97
	v_mov_b64_e32 v[30:31], v[14:15]
	s_waitcnt vmcnt(1)
	v_mov_b64_e32 v[86:87], v[82:83]
	s_mov_b32 s45, 0
	v_lshlrev_b32_e32 v119, 10, v111
	v_lshlrev_b32_e32 v120, 4, v110
	v_lshl_add_u32 v118, v110, 2, s96
	s_add_i32 s47, s26, 0x10bfc
	s_addk_i32 s48, 0xff
	v_mov_b32_e32 v123, 0xf149f2ca
	v_mov_b32_e32 v122, 0
	s_mov_b32 s61, 0
	v_mov_b64_e32 v[28:29], v[12:13]
	v_mov_b64_e32 v[26:27], v[10:11]
	v_mov_b64_e32 v[24:25], v[8:9]
	v_mov_b64_e32 v[22:23], v[6:7]
	v_mov_b64_e32 v[20:21], v[4:5]
	v_mov_b64_e32 v[18:19], v[2:3]
	s_waitcnt vmcnt(0)
	v_mov_b64_e32 v[88:89], v[92:93]
	v_mov_b64_e32 v[16:17], v[0:1]
	v_mov_b64_e32 v[84:85], v[80:81]
	v_mov_b64_e32 v[90:91], v[94:95]
	s_add_i32 s51, s49, -1
	s_cmp_lt_u32 s51, 2
	s_cbranch_scc1 .LBB0_289
	s_branch .LBB0_288

.LBB0_295:
	s_nop 8
	v_max3_f32 v124, v33, v49, v34
	v_max3_f32 v125, v50, v35, v51
	v_max3_f32 v126, v48, v32, v36
	v_max3_f32 v127, v52, v37, v53
	v_max3_f32 v124, v124, v38, v54
	v_max3_f32 v125, v125, v39, v55
	v_max3_f32 v126, v126, v40, v56
	v_max3_f32 v127, v127, v41, v57
	v_max3_f32 v124, v124, v42, v58
	v_max3_f32 v125, v125, v43, v59
	v_max3_f32 v126, v126, v44, v60
	v_max3_f32 v127, v127, v45, v61
	v_max3_f32 v124, v124, v46, v62
	v_max3_f32 v125, v125, v47, v63
	v_max3_f32 v124, v124, v125, v126
	v_max_f32_e32 v124, v124, v127
	v_mov_b32_e32 v125, v124
	s_nop 1
	v_permlane32_swap_b32_e32 v125, v124
	s_waitcnt lgkmcnt(0)
	v_max3_f32 v124, v123, v124, v125
	v_sub_f32_e32 v123, v123, v124
	v_exp_f32_e32 v123, v123
	s_nop 0
	v_cmp_eq_f32_e32 vcc, 1.0, v123
	s_cmp_eq_u64 vcc, exec
	s_cbranch_scc1 .LBB0_299
	s_and_saveexec_b64 s[84:85], s[20:21]
	ds_write_b32 v118, v123 offset:32768
	s_or_b64 exec, exec, s[84:85]
	v_add_u32_e32 v125, s96, v98
	ds_read_b128 v[126:129], v125 offset:32864
	ds_read_b128 v[130:133], v125 offset:32832
	ds_read_b128 v[134:137], v125 offset:32800
	ds_read_b128 v[138:141], v125 offset:32768
	s_waitcnt lgkmcnt(3)
	v_pk_mul_f32 v[12:13], v[12:13], v[126:127]
	s_waitcnt lgkmcnt(2)
	v_pk_mul_f32 v[8:9], v[8:9], v[130:131]
	s_waitcnt lgkmcnt(1)
	v_pk_mul_f32 v[4:5], v[4:5], v[134:135]
	v_pk_mul_f32 v[14:15], v[14:15], v[128:129]
	v_pk_mul_f32 v[10:11], v[10:11], v[132:133]
	v_pk_mul_f32 v[6:7], v[6:7], v[136:137]
	s_waitcnt lgkmcnt(0)
	v_pk_mul_f32 v[2:3], v[2:3], v[140:141]
	v_pk_mul_f32 v[0:1], v[0:1], v[138:139]
	v_pk_mul_f32 v[28:29], v[28:29], v[126:127]
	v_pk_mul_f32 v[24:25], v[24:25], v[130:131]
	v_pk_mul_f32 v[20:21], v[20:21], v[134:135]
	v_pk_mul_f32 v[30:31], v[30:31], v[128:129]
	v_pk_mul_f32 v[26:27], v[26:27], v[132:133]
	v_pk_mul_f32 v[22:23], v[22:23], v[136:137]
	v_pk_mul_f32 v[18:19], v[18:19], v[140:141]
	v_pk_mul_f32 v[16:17], v[16:17], v[138:139]

.LBB0_302:
	s_add_i32 s99, s98, 4
	s_cmp_eq_u32 s99, 12
	s_cselect_b32 s99, 0, s99
	v_mov_b32_e32 v32, 0x21a00
	v_add_u32_e32 v33, s99, v32
	v_add_u32_e32 v32, s98, v32
	v_mov_b32_e32 v34, 1
	v_mov_b32_e32 v35, 0
	ds_write_b32 v33, v34
	s_cmp_lg_u32 s61, 0
	s_cbranch_scc1 .Lfox_vote_keep
	ds_write_b32 v32, v35
.Lfox_vote_keep:
	s_mov_b32 s98, s99
	s_waitcnt lgkmcnt(0)
	s_barrier
	ds_read_b32 v32, v32
	s_waitcnt lgkmcnt(0)
	v_cmp_ne_u32_e32 vcc, 0, v32
	s_mov_b64 s[84:85], -1
	s_cbranch_vccnz .LBB0_311

.LBB0_3833:
	s_nop 8
	v_max3_f32 v47, v3, v19, v4
	v_max3_f32 v53, v20, v5, v21
	v_max3_f32 v54, v18, v2, v6
	v_max3_f32 v55, v22, v7, v23
	v_max3_f32 v47, v47, v8, v24
	v_max3_f32 v53, v53, v9, v25
	v_max3_f32 v54, v54, v10, v26
	v_max3_f32 v55, v55, v11, v27
	v_max3_f32 v47, v47, v12, v28
	v_max3_f32 v53, v53, v13, v29
	v_max3_f32 v54, v54, v14, v30
	v_max3_f32 v55, v55, v15, v31
	v_max3_f32 v47, v47, v16, v32
	v_max3_f32 v53, v53, v17, v33
	v_max3_f32 v47, v47, v53, v54
	v_max_f32_e32 v47, v47, v55
	v_mov_b32_e32 v53, v47
	s_nop 1
	v_permlane32_swap_b32_e32 v53, v47
	s_add_i32 s10, s10, 1
	s_cmp_ge_u32 s10, s15
	s_cbranch_scc1 .LBB0_3835
	s_and_b32 s13, s11, 0x4000
	v_add_u32_e32 v54, s13, v184
	ds_write_b128 v54, v[38:41]

.LBB0_3846:
	s_nop 5
	s_nop 1
	v_mov_b32_dpp v54, v151 quad_perm:[1,0,3,2] row_mask:0xf bank_mask:0xf
	s_nop 1
	v_mov_b32_dpp v59, v159 quad_perm:[1,0,3,2] row_mask:0xf bank_mask:0xf
	s_nop 1
	v_mov_b32_dpp v63, v187 quad_perm:[1,0,3,2] row_mask:0xf bank_mask:0xf
	s_nop 1
	v_mov_b32_dpp v68, v195 quad_perm:[1,0,3,2] row_mask:0xf bank_mask:0xf
	v_add_f32_e32 v50, v144, v146
	s_waitcnt lgkmcnt(3)
	v_add_f32_e32 v54, v151, v54
	s_waitcnt lgkmcnt(2)
	v_add_f32_e32 v59, v159, v59
	s_waitcnt lgkmcnt(1)
	v_add_f32_e32 v63, v187, v63
	s_nop 1
	v_mov_b32_dpp v55, v54 quad_perm:[2,3,0,1] row_mask:0xf bank_mask:0xf
	s_nop 1
	v_mov_b32_dpp v60, v59 quad_perm:[2,3,0,1] row_mask:0xf bank_mask:0xf
	s_nop 1
	v_mov_b32_dpp v64, v63 quad_perm:[2,3,0,1] row_mask:0xf bank_mask:0xf
	s_waitcnt lgkmcnt(3)
	v_add_f32_e32 v68, v195, v68
	s_nop 1
	v_mov_b32_dpp v71, v68 quad_perm:[2,3,0,1] row_mask:0xf bank_mask:0xf
	s_waitcnt lgkmcnt(3)
	v_add_f32_e32 v58, v54, v55
	s_nop 1
	v_mov_b32_dpp v54, v152 quad_perm:[1,0,3,2] row_mask:0xf bank_mask:0xf
	s_waitcnt lgkmcnt(3)
	v_add_f32_e32 v69, v59, v60
	s_nop 1
	v_mov_b32_dpp v59, v162 quad_perm:[1,0,3,2] row_mask:0xf bank_mask:0xf
	s_waitcnt lgkmcnt(3)
	v_add_f32_e32 v72, v63, v64
	s_nop 1
	v_mov_b32_dpp v63, v188 quad_perm:[1,0,3,2] row_mask:0xf bank_mask:0xf
	s_waitcnt lgkmcnt(2)
	v_add_f32_e32 v54, v152, v54
	s_nop 1
	v_mov_b32_dpp v55, v54 quad_perm:[2,3,0,1] row_mask:0xf bank_mask:0xf
	s_waitcnt lgkmcnt(2)
	v_add_f32_e32 v59, v162, v59
	s_nop 1
	v_mov_b32_dpp v60, v59 quad_perm:[2,3,0,1] row_mask:0xf bank_mask:0xf
	s_waitcnt lgkmcnt(2)
	v_add_f32_e32 v63, v188, v63
	s_nop 1
	v_mov_b32_dpp v64, v63 quad_perm:[2,3,0,1] row_mask:0xf bank_mask:0xf
	v_add_f32_e32 v75, v68, v71
	s_nop 1
	v_mov_b32_dpp v68, v196 quad_perm:[1,0,3,2] row_mask:0xf bank_mask:0xf
	v_add_f32_e32 v51, v148, v151
	v_add_f32_e32 v52, v145, v147
	v_add_f32_e32 v53, v150, v152
	s_waitcnt lgkmcnt(3)
	v_add_f32_e32 v67, v54, v55
	v_add_f32_e32 v54, v153, v155
	v_add_f32_e32 v55, v157, v159
	v_add_f32_e32 v56, v154, v156
	v_add_f32_e32 v57, v158, v162
	s_waitcnt lgkmcnt(2)
	v_add_f32_e32 v70, v59, v60
	v_add_f32_e32 v59, v163, v165
	v_add_f32_e32 v60, v167, v187
	v_add_f32_e32 v61, v164, v166
	v_add_f32_e32 v62, v186, v188
	s_waitcnt lgkmcnt(1)
	v_add_f32_e32 v74, v63, v64
	v_add_f32_e32 v63, v189, v191
	v_add_f32_e32 v64, v193, v195
	v_add_f32_e32 v65, v190, v192
	v_add_f32_e32 v66, v194, v196
	v_add_f32_e32 v50, v50, v51
	v_add_f32_e32 v52, v52, v53
	v_add_f32_e32 v54, v54, v55
	v_add_f32_e32 v56, v56, v57
	v_add_f32_e32 v59, v59, v60
	v_add_f32_e32 v61, v61, v62
	v_add_f32_e32 v63, v63, v64
	v_add_f32_e32 v65, v65, v66
	s_waitcnt lgkmcnt(0)
	v_add_f32_e32 v68, v196, v68
	s_nop 1
	v_mov_b32_dpp v51, v50 quad_perm:[1,0,3,2] row_mask:0xf bank_mask:0xf
	s_nop 1
	v_mov_b32_dpp v53, v52 quad_perm:[1,0,3,2] row_mask:0xf bank_mask:0xf
	s_nop 1
	v_mov_b32_dpp v55, v54 quad_perm:[1,0,3,2] row_mask:0xf bank_mask:0xf
	s_nop 1
	v_mov_b32_dpp v57, v56 quad_perm:[1,0,3,2] row_mask:0xf bank_mask:0xf
	s_nop 1
	v_mov_b32_dpp v60, v59 quad_perm:[1,0,3,2] row_mask:0xf bank_mask:0xf
	s_nop 1
	v_mov_b32_dpp v62, v61 quad_perm:[1,0,3,2] row_mask:0xf bank_mask:0xf
	s_nop 1
	v_mov_b32_dpp v64, v63 quad_perm:[1,0,3,2] row_mask:0xf bank_mask:0xf
	s_nop 1
	v_mov_b32_dpp v66, v65 quad_perm:[1,0,3,2] row_mask:0xf bank_mask:0xf
	s_nop 1
	v_mov_b32_dpp v71, v68 quad_perm:[2,3,0,1] row_mask:0xf bank_mask:0xf
	s_waitcnt lgkmcnt(8)
	v_add_f32_e32 v50, v50, v51
	s_waitcnt lgkmcnt(7)
	v_add_f32_e32 v52, v52, v53
	s_waitcnt lgkmcnt(6)
	v_add_f32_e32 v54, v54, v55
	s_waitcnt lgkmcnt(5)
	v_add_f32_e32 v56, v56, v57
	s_waitcnt lgkmcnt(4)
	v_add_f32_e32 v59, v59, v60
	s_waitcnt lgkmcnt(3)
	v_add_f32_e32 v61, v61, v62
	s_waitcnt lgkmcnt(2)
	v_add_f32_e32 v63, v63, v64
	s_waitcnt lgkmcnt(1)
	v_add_f32_e32 v65, v65, v66
	s_waitcnt lgkmcnt(0)
	v_add_f32_e32 v76, v68, v71
	s_nop 1
	v_mov_b32_dpp v51, v50 quad_perm:[2,3,0,1] row_mask:0xf bank_mask:0xf
	s_nop 1
	v_mov_b32_dpp v53, v52 quad_perm:[2,3,0,1] row_mask:0xf bank_mask:0xf
	s_nop 1
	v_mov_b32_dpp v55, v54 quad_perm:[2,3,0,1] row_mask:0xf bank_mask:0xf
	s_nop 1
	v_mov_b32_dpp v57, v56 quad_perm:[2,3,0,1] row_mask:0xf bank_mask:0xf
	s_nop 1
	v_mov_b32_dpp v60, v59 quad_perm:[2,3,0,1] row_mask:0xf bank_mask:0xf
	s_nop 1
	v_mov_b32_dpp v62, v61 quad_perm:[2,3,0,1] row_mask:0xf bank_mask:0xf
	s_nop 1
	v_mov_b32_dpp v64, v63 quad_perm:[2,3,0,1] row_mask:0xf bank_mask:0xf
	s_nop 1
	v_mov_b32_dpp v66, v65 quad_perm:[2,3,0,1] row_mask:0xf bank_mask:0xf
	ds_bpermute_b32 v68, v179, v58
	ds_bpermute_b32 v67, v179, v67
	ds_bpermute_b32 v71, v179, v69
	ds_bpermute_b32 v69, v179, v70
	ds_bpermute_b32 v73, v179, v72
	ds_bpermute_b32 v72, v179, v74
	ds_bpermute_b32 v70, v179, v75
	ds_bpermute_b32 v58, v179, v76
	s_and_saveexec_b64 s[12:13], s[10:11]
	s_cbranch_execz .LBB0_3848
	s_waitcnt lgkmcnt(1)
	v_cndmask_b32_e64 v74, v70, v73, s[8:9]
	v_cndmask_b32_e64 v73, v73, v71, s[8:9]
	v_cndmask_b32_e64 v71, v71, v68, s[8:9]
	v_cndmask_b32_e64 v68, v68, v141, s[8:9]
	v_add_f32_e32 v50, v50, v51
	v_add_u32_e32 v51, s18, v143
	s_waitcnt lgkmcnt(0)
	v_cndmask_b32_e64 v75, v58, v72, s[8:9]
	v_cndmask_b32_e64 v72, v72, v69, s[8:9]
	v_cndmask_b32_e64 v69, v69, v67, s[8:9]
	v_cndmask_b32_e64 v67, v67, v70, s[8:9]
	v_add_f32_e32 v52, v52, v53
	v_add_u32_e32 v53, 0x10800, v51
	v_add_f32_e32 v50, v50, v68
	v_add_f32_e32 v54, v54, v55
	ds_write_b32 v53, v50
	v_add_f32_e32 v50, v52, v67
	v_add_u32_e32 v52, 0x10820, v51
	v_add_f32_e32 v56, v56, v57
	ds_write_b32 v52, v50
	v_add_f32_e32 v50, v54, v71
	v_add_u32_e32 v52, 0x10808, v51
	v_add_f32_e32 v59, v59, v60
	ds_write_b32 v52, v50
	v_add_f32_e32 v50, v56, v69
	v_add_u32_e32 v52, 0x10828, v51
	v_add_f32_e32 v61, v61, v62
	ds_write_b32 v52, v50
	v_add_f32_e32 v50, v59, v73
	v_add_u32_e32 v52, 0x10810, v51
	v_add_f32_e32 v63, v63, v64
	ds_write_b32 v52, v50
	v_add_f32_e32 v50, v61, v72
	v_add_u32_e32 v52, 0x10830, v51
	v_add_f32_e32 v65, v65, v66
	ds_write_b32 v52, v50
	v_add_f32_e32 v50, v63, v74
	v_add_u32_e32 v52, 0x10818, v51
	ds_write_b32 v52, v50
	v_add_f32_e32 v50, v65, v75
	v_add_u32_e32 v51, 0x10838, v51
	ds_write_b32 v51, v50

.LBB0_4169:
	s_nop 3
	v_max3_f32 v1, v35, v51, v36
	v_max3_f32 v108, v52, v37, v53
	v_max3_f32 v109, v50, v34, v38
	v_max3_f32 v110, v54, v39, v55
	v_max3_f32 v1, v1, v40, v56
	v_max3_f32 v108, v108, v41, v57
	v_max3_f32 v109, v109, v42, v58
	v_max3_f32 v110, v110, v43, v59
	v_max3_f32 v1, v1, v44, v60
	v_max3_f32 v108, v108, v45, v61
	v_max3_f32 v109, v109, v46, v62
	v_max3_f32 v110, v110, v47, v63
	v_max3_f32 v1, v1, v48, v64
	v_max3_f32 v108, v108, v49, v65
	v_max3_f32 v1, v1, v108, v109
	v_max_f32_e32 v1, v1, v110
	v_mov_b32_e32 v108, v1
	s_nop 1
	v_permlane32_swap_b32_e32 v108, v1
	s_waitcnt lgkmcnt(0)
	v_max3_f32 v1, v107, v1, v108
	v_sub_f32_e32 v107, v107, v1
	v_exp_f32_e32 v107, v107
	s_nop 0
	v_cmp_eq_f32_e32 vcc, 1.0, v107
	s_cmp_eq_u64 vcc, exec
	s_cbranch_scc1 .LBB0_4173
	s_and_saveexec_b64 s[10:11], s[8:9]
	ds_write_b32 v104, v107 offset:32768
	s_or_b64 exec, exec, s[10:11]
	ds_read_b128 v[108:111], v105 offset:32864
	ds_read_b128 v[112:115], v105 offset:32832
	ds_read_b128 v[116:119], v105 offset:32800
	ds_read_b128 v[120:123], v105 offset:32768
	s_waitcnt lgkmcnt(3)
	v_pk_mul_f32 v[30:31], v[30:31], v[108:109]
	s_waitcnt lgkmcnt(2)
	v_pk_mul_f32 v[26:27], v[26:27], v[112:113]
	s_waitcnt lgkmcnt(1)
	v_pk_mul_f32 v[22:23], v[22:23], v[116:117]
	s_waitcnt lgkmcnt(0)
	v_pk_mul_f32 v[18:19], v[18:19], v[120:121]
	v_pk_mul_f32 v[14:15], v[14:15], v[108:109]
	v_pk_mul_f32 v[10:11], v[10:11], v[112:113]
	v_pk_mul_f32 v[6:7], v[6:7], v[116:117]
	v_pk_mul_f32 v[32:33], v[32:33], v[110:111]
	v_pk_mul_f32 v[28:29], v[28:29], v[114:115]
	v_pk_mul_f32 v[24:25], v[24:25], v[118:119]
	v_pk_mul_f32 v[20:21], v[20:21], v[122:123]
	v_pk_mul_f32 v[16:17], v[16:17], v[110:111]
	v_pk_mul_f32 v[12:13], v[12:13], v[114:115]
	v_pk_mul_f32 v[8:9], v[8:9], v[118:119]
	v_pk_mul_f32 v[4:5], v[4:5], v[122:123]
	v_pk_mul_f32 v[2:3], v[2:3], v[120:121]
